# grid barrier: top-level last arriver fans the release out to 16 per-XCD words; non-leader WGs spin on their own XCD word instead of the single TOPGEN line
# speedup vs baseline: 1.0045x; 1.0022x over previous
.LBB0_5:
	s_or_b64 exec, exec, s[6:7]
	s_load_dwordx2 s[6:7], s[78:79], 0xd0
	s_waitcnt lgkmcnt(0)
	v_writelane_b32 v254, s6, 3
	s_nop 1
	v_writelane_b32 v254, s7, 4
	s_cmp_ge_i32 s6, s7
	s_cbranch_scc1 .LBB0_1209
	s_add_u32 s74, s78, 0xd8
	s_addc_u32 s75, s79, 0
	s_cmp_lg_u32 0, -1
	s_cselect_b64 s[6:7], -1, 0
	v_writelane_b32 v254, s6, 5
	v_lshrrev_b32_e32 v1, 20, v0
	v_lshrrev_b32_e32 v0, 10, v0
	v_writelane_b32 v254, s7, 6
	v_or_b32_e32 v0, v0, v1
	v_readlane_b32 s6, v254, 0
	s_ashr_i32 s3, s6, 31
	v_writelane_b32 v254, s3, 7
	s_lshr_b32 s3, s3, 29
	s_add_i32 s3, s6, s3
	s_ashr_i32 s7, s3, 3
	s_and_b32 s3, s3, -8
	v_writelane_b32 v254, s7, 8
	s_sub_i32 s3, s6, s3
	v_writelane_b32 v254, s3, 9
	s_lshr_b32 s3, s3, 31
	s_add_u32 s6, s0, 0x13c56400
	v_writelane_b32 v254, s3, 10
	s_addc_u32 s7, s1, 0
	v_writelane_b32 v254, s6, 11
	v_mov_b32_e32 v173, 0
	v_mov_b64_e32 v[174:175], 0x800
	v_writelane_b32 v254, s7, 12
	s_add_u32 s6, s0, 0x13c56600
	s_addc_u32 s7, s1, 0
	v_writelane_b32 v254, s6, 13
	v_mov_b32_e32 v176, 0x358637bd
	v_mov_b32_e32 v191, 0x3ecc95a3
	v_writelane_b32 v254, s7, 14
	s_add_u32 s6, s0, 0x13c56700
	s_addc_u32 s7, s1, 0
	v_writelane_b32 v254, s6, 15
	v_mov_b32_e32 v193, 0x3c0881c4
	v_mov_b32_e32 v195, 0xbab64f3b
	v_writelane_b32 v254, s7, 16
	s_add_u32 s6, s0, 0x13c56800
	s_addc_u32 s7, s1, 0
	v_writelane_b32 v254, s6, 17
	v_bfrev_b32_e32 v223, 0.5
	v_mov_b32_e32 v224, 0xf149f2ca
	v_writelane_b32 v254, s7, 18
	s_add_u32 s6, s0, 0x13c56900
	s_addc_u32 s7, s1, 0
	v_writelane_b32 v254, s6, 19
	v_mov_b32_e32 v226, 0x182
	v_mov_b32_e32 v178, 0x3f317218
	v_writelane_b32 v254, s7, 20
	s_add_u32 s6, s0, 0x13c56a00
	s_addc_u32 s7, s1, 0
	v_writelane_b32 v254, s6, 21
	v_mov_b32_e32 v227, 0x7f800000
	v_mov_b32_e32 v228, 0x7fc00000
	v_writelane_b32 v254, s7, 22
	s_add_u32 s6, s0, 0x13c56b00
	s_addc_u32 s7, s1, 0
	v_writelane_b32 v254, s6, 23
	v_mov_b32_e32 v229, 0xff800000
	v_mov_b64_e32 v[180:181], 0x13c10200
	v_writelane_b32 v254, s7, 24
	s_add_u32 s6, s0, 0x13c56c00
	s_addc_u32 s7, s1, 0
	v_writelane_b32 v254, s6, 25
	v_mov_b32_e32 v225, 0x40000
	v_not_b32_e32 v222, 63
	v_writelane_b32 v254, s7, 26
	s_add_u32 s6, s0, 0x13c56d00
	s_addc_u32 s7, s1, 0
	v_writelane_b32 v254, s6, 27
	v_not_b32_e32 v232, 31
	s_movk_i32 s97, 0x80
	v_writelane_b32 v254, s7, 28
	s_add_u32 s6, s0, 0x13c56e00
	s_addc_u32 s7, s1, 0
	v_writelane_b32 v254, s6, 29
	s_movk_i32 s73, 0x1000
	s_mov_b32 s88, 0x800000
	v_writelane_b32 v254, s7, 30
	s_add_u32 s6, s0, 0x13c56f00
	s_addc_u32 s7, s1, 0
	v_writelane_b32 v254, s6, 31
	s_movk_i32 s89, 0x110
	s_movk_i32 s21, 0x183
	v_writelane_b32 v254, s7, 32
	s_add_u32 s6, s0, 0x13c57000
	s_addc_u32 s7, s1, 0
	v_writelane_b32 v254, s6, 33
	s_mov_b32 s13, 0xfe03f81
	s_movk_i32 s16, 0xff7f
	v_writelane_b32 v254, s7, 34
	s_add_u32 s6, s0, 0x13c57100
	s_addc_u32 s7, s1, 0
	v_writelane_b32 v254, s6, 35
	s_movk_i32 s18, 0x81
	s_movk_i32 s14, 0x100
	v_writelane_b32 v254, s7, 36
	s_add_u32 s6, s0, 0x13c57200
	s_addc_u32 s7, s1, 0
	v_writelane_b32 v254, s6, 37
	s_movk_i32 s37, 0x5200
	s_mov_b32 s90, 0x41a00000
	v_writelane_b32 v254, s7, 38
	s_add_u32 s6, s0, 0x13c57300
	s_addc_u32 s7, s1, 0
	v_writelane_b32 v254, s6, 39
	s_movk_i32 s23, 0x6000
	s_mov_b32 s19, 0xc000
	v_writelane_b32 v254, s7, 40
	s_add_u32 s6, s0, 0x13c57400
	s_addc_u32 s7, s1, 0
	v_writelane_b32 v254, s6, 41
	s_mov_b32 s33, 0x12000
	s_mov_b32 s22, 0x5040100
	v_writelane_b32 v254, s7, 42
	s_add_u32 s6, s0, 0x13c57500
	s_addc_u32 s7, s1, 0
	v_writelane_b32 v254, s6, 43
	s_cmp_eq_u32 s2, 15
	s_mov_b32 s36, 0x1e579000
	v_writelane_b32 v254, s7, 44
	s_cselect_b64 s[6:7], -1, 0
	v_writelane_b32 v254, s6, 45
	s_cmp_eq_u32 s2, 14
	s_mov_b32 s12, 0x22579000
	v_writelane_b32 v254, s7, 46
	s_cselect_b64 s[6:7], -1, 0
	v_writelane_b32 v254, s6, 47
	s_cmp_eq_u32 s2, 13
	s_mov_b32 s31, 0
	v_writelane_b32 v254, s7, 48
	s_cselect_b64 s[6:7], -1, 0
	v_writelane_b32 v254, s6, 49
	s_cmp_eq_u32 s2, 12
	s_mov_b64 s[34:35], 0x800
	v_writelane_b32 v254, s7, 50
	s_cselect_b64 s[6:7], -1, 0
	v_writelane_b32 v254, s6, 51
	s_cmp_eq_u32 s2, 11
	s_mov_b64 s[38:39], 0x800000
	v_writelane_b32 v254, s7, 52
	s_cselect_b64 s[6:7], -1, 0
	v_writelane_b32 v254, s6, 53
	s_cmp_eq_u32 s2, 10
	s_mov_b64 s[54:55], 0x80
	v_writelane_b32 v254, s7, 54
	s_cselect_b64 s[6:7], -1, 0
	v_writelane_b32 v254, s6, 55
	s_cmp_eq_u32 s2, 9
	s_nop 0
	v_writelane_b32 v254, s7, 56
	s_cselect_b64 s[6:7], -1, 0
	v_writelane_b32 v254, s6, 57
	s_cmp_eq_u32 s2, 8
	s_nop 0
	v_writelane_b32 v254, s7, 58
	s_cselect_b64 s[6:7], -1, 0
	v_writelane_b32 v254, s6, 59
	s_cmp_eq_u32 s2, 7
	s_nop 0
	v_writelane_b32 v254, s7, 60
	s_cselect_b64 s[6:7], -1, 0
	v_writelane_b32 v254, s6, 61
	s_cmp_eq_u32 s2, 6
	s_nop 0
	v_writelane_b32 v254, s7, 62
	s_cselect_b64 s[6:7], -1, 0
	v_writelane_b32 v254, s6, 63
	s_cmp_eq_u32 s2, 5
	s_nop 0
	v_writelane_b32 v255, s7, 0
	s_cselect_b64 s[6:7], -1, 0
	v_writelane_b32 v255, s6, 1
	s_cmp_eq_u32 s2, 4
	s_nop 0
	v_writelane_b32 v255, s7, 2
	s_cselect_b64 s[6:7], -1, 0
	v_writelane_b32 v255, s6, 3
	s_cmp_eq_u32 s2, 3
	s_nop 0
	v_writelane_b32 v255, s7, 4
	s_cselect_b64 s[6:7], -1, 0
	v_writelane_b32 v255, s6, 5
	s_cmp_eq_u32 s2, 2
	s_nop 0
	v_writelane_b32 v255, s7, 6
	s_cselect_b64 s[6:7], -1, 0
	v_writelane_b32 v255, s6, 7
	s_cmp_eq_u32 s2, 1
	s_nop 0
	v_writelane_b32 v255, s7, 8
	s_cselect_b64 s[6:7], -1, 0
	v_writelane_b32 v255, s6, 9
	s_cmp_eq_u32 s2, 0
	s_nop 0
	v_writelane_b32 v255, s7, 10
	s_cselect_b64 s[6:7], -1, 0
	s_add_u32 s98, s4, 0x2400
	s_addc_u32 s99, s5, 0
	v_writelane_b32 v255, s98, 51
	v_writelane_b32 v255, s99, 52
	s_nop 0
	s_nop 0
	s_nop 0
	s_nop 0
	s_nop 0
	s_nop 0
	s_nop 0
	s_nop 0
	s_nop 0
	s_lshl_b32 s2, s2, 8
	s_add_u32 s2, s4, s2
	s_addc_u32 s3, s5, 0
	v_writelane_b32 v255, s6, 11
	s_add_u32 s4, s2, 0x1400
	s_addc_u32 s5, s3, 0
	v_writelane_b32 v255, s7, 12
	v_writelane_b32 v255, s4, 13
	s_add_u32 s2, s2, 0x2400
	s_addc_u32 s3, s3, 0
	v_writelane_b32 v255, s5, 14
	v_writelane_b32 v255, s2, 15
	s_nop 1
	v_writelane_b32 v255, s3, 16
	s_add_u32 s2, s0, 0x13c59600
	s_addc_u32 s3, s1, 0
	v_writelane_b32 v255, s2, 17
	s_add_u32 s0, s0, 0x13c59700
	s_addc_u32 s1, s1, 0
	v_writelane_b32 v255, s3, 18
	v_writelane_b32 v255, s0, 19
	s_add_i32 s3, 0, 0x14000
	s_nop 0
	v_writelane_b32 v255, s1, 20
	s_movk_i32 s0, 0x3ff
	v_and_or_b32 v0, v0, s0, v177
	s_add_i32 s0, 0, 0x13000
	v_writelane_b32 v255, s0, 21
	s_add_i32 s0, 0, 0xa800
	v_writelane_b32 v255, s0, 22
	s_add_i32 s0, 0, 0x20004
	v_writelane_b32 v255, s0, 23
	s_load_dwordx2 s[0:1], s[78:79], 0xd0
	s_waitcnt lgkmcnt(0)
	s_mov_b32 s10, s0
	v_cmp_eq_u32_e64 s[0:1], 0, v0
	s_nop 1
	v_writelane_b32 v255, s0, 24
	s_nop 1
	v_writelane_b32 v255, s1, 25
	v_writelane_b32 v255, s78, 26
	s_nop 1
	v_writelane_b32 v255, s79, 27
	v_writelane_b32 v255, s74, 28
	s_nop 1
	v_writelane_b32 v255, s75, 29
	s_branch .LBB0_11

.LBB0_1193:
	s_or_b64 exec, exec, s[4:5]
	s_and_saveexec_b64 s[4:5], s[6:7]
	s_cbranch_execz .LBB0_1195
	v_mov_b32_e32 v2, 1
	global_atomic_add v[0:1], v2, off
	s_branch .LBB0_1195
.Lxb_fan:
	s_or_b64 exec, exec, s[4:5]
	v_readlane_b32 s8, v255, 51
	v_readlane_b32 s9, v255, 52
	v_mov_b32_e32 v2, 1
	global_atomic_add v[0:1], v2, off
	s_nop 4
	global_atomic_add v173, v2, s[8:9]
	global_atomic_add v173, v2, s[8:9] offset:256
	global_atomic_add v173, v2, s[8:9] offset:512
	global_atomic_add v173, v2, s[8:9] offset:768
	global_atomic_add v173, v2, s[8:9] offset:1024
	global_atomic_add v173, v2, s[8:9] offset:1280
	global_atomic_add v173, v2, s[8:9] offset:1536
	global_atomic_add v173, v2, s[8:9] offset:1792
	global_atomic_add v173, v2, s[8:9] offset:2048
	global_atomic_add v173, v2, s[8:9] offset:2304
	global_atomic_add v173, v2, s[8:9] offset:2560
	global_atomic_add v173, v2, s[8:9] offset:2816
	global_atomic_add v173, v2, s[8:9] offset:3072
	global_atomic_add v173, v2, s[8:9] offset:3328
	global_atomic_add v173, v2, s[8:9] offset:3584
	global_atomic_add v173, v2, s[8:9] offset:3840
